# v49 + x-copy loop: both Params pointer s_loads issued together (one scalar round trip per iteration instead of two)
# speedup vs baseline: 1.0033x; 1.0033x over previous
.LBB0_492:
	s_load_dwordx2 s[0:1], s[58:59], 0x0
	s_load_dwordx2 s[40:41], s[58:59], 0xb8
	s_waitcnt lgkmcnt(0)
	v_lshl_add_u64 v[20:21], s[0:1], 0, v[8:9]
	global_load_dwordx4 v[16:19], v[20:21], off
	global_load_dwordx4 v[26:29], v[20:21], off offset:1024
	global_load_dwordx4 v[30:33], v[20:21], off offset:2048
	global_load_dwordx4 v[34:37], v[20:21], off offset:3072
	v_lshl_add_u64 v[22:23], s[40:41], 0, v[8:9]
	s_mov_b32 s0, 0x2080000
	s_waitcnt vmcnt(3)
	v_mul_f32_e32 v0, v17, v17
	v_fmac_f32_e32 v0, v16, v16
	v_fmac_f32_e32 v0, v18, v18
	v_fmac_f32_e32 v0, v19, v19
	global_store_dwordx4 v[22:23], v[16:19], off
	s_nop 1
	v_cvt_pk_bf16_f32 v16, v16, v17
	v_cvt_pk_bf16_f32 v17, v18, v19
	v_lshl_add_u64 v[18:19], s[14:15], 0, v[6:7]
	v_add_co_u32_e64 v24, s[40:41], s0, v18
	s_nop 1
	v_addc_co_u32_e64 v25, s[40:41], 0, v19, s[40:41]
	global_store_dwordx2 v[24:25], v[16:17], off
	s_waitcnt vmcnt(4)
	v_mul_f32_e32 v3, v27, v27
	v_fmac_f32_e32 v3, v26, v26
	global_store_dwordx4 v[22:23], v[26:29], off offset:1024
	v_fmac_f32_e32 v3, v28, v28
	v_fmac_f32_e32 v3, v29, v29
	v_cvt_pk_bf16_f32 v26, v26, v27
	v_cvt_pk_bf16_f32 v27, v28, v29
	global_store_dwordx2 v[24:25], v[26:27], off offset:512
	v_add_f32_e32 v0, v0, v3
	s_waitcnt vmcnt(5)
	v_mul_f32_e32 v3, v31, v31
	v_fmac_f32_e32 v3, v30, v30
	global_store_dwordx4 v[22:23], v[30:33], off offset:2048
	v_fmac_f32_e32 v3, v32, v32
	v_fmac_f32_e32 v3, v33, v33
	v_cvt_pk_bf16_f32 v30, v30, v31
	v_cvt_pk_bf16_f32 v31, v32, v33
	global_store_dwordx2 v[24:25], v[30:31], off offset:1024
	v_add_f32_e32 v0, v0, v3
	s_waitcnt vmcnt(6)
	v_mul_f32_e32 v3, v35, v35
	v_fmac_f32_e32 v3, v34, v34
	v_fmac_f32_e32 v3, v36, v36
	v_fmac_f32_e32 v3, v37, v37
	v_add_f32_e32 v0, v0, v3
	ds_bpermute_b32 v3, v10, v0
	global_store_dwordx4 v[22:23], v[34:37], off offset:3072
	s_waitcnt lgkmcnt(0)
	v_add_f32_e32 v0, v0, v3
	ds_bpermute_b32 v3, v11, v0
	v_cvt_pk_bf16_f32 v34, v34, v35
	v_cvt_pk_bf16_f32 v35, v36, v37
	global_store_dwordx2 v[24:25], v[34:35], off offset:1536
	s_waitcnt lgkmcnt(0)
	v_add_f32_e32 v0, v0, v3
	ds_bpermute_b32 v3, v12, v0
	s_waitcnt lgkmcnt(0)
	v_add_f32_e32 v0, v0, v3
	ds_bpermute_b32 v3, v13, v0
	s_waitcnt lgkmcnt(0)
	v_add_f32_e32 v0, v0, v3
	ds_bpermute_b32 v3, v14, v0
	s_waitcnt lgkmcnt(0)
	v_add_f32_e32 v0, v0, v3
	ds_bpermute_b32 v3, v15, v0
	s_and_saveexec_b64 s[6:7], vcc
	s_cbranch_execz .LBB0_491
	s_waitcnt lgkmcnt(0)
	v_add_f32_e32 v0, v0, v3
	v_cndmask_b32_e64 v0, 0, v0, s[38:39]
	v_lshl_add_u64 v[16:17], s[14:15], 0, v[4:5]
	global_store_dword v[16:17], v0, off
	s_branch .LBB0_491
